# RWKV producer: cache-warming loads two chunks ahead, bottom drain counted (vmcnt 16)
# baseline (speedup 1.0000x reference)
.LBB0_765:
	s_or_b64 exec, exec, s[8:9]
	s_cmp_eq_u32 s62, 0x10000
	s_cbranch_scc1 .LBB0_777
	s_cmpk_lt_u32 s63, 0x7f
	s_cselect_b64 s[44:45], -1, 0
	s_cmpk_gt_u32 s63, 0x7e
	v_lshl_add_u64 v[134:135], s[66:67], 0, v[82:83]
	v_lshl_add_u64 v[132:133], s[66:67], 0, v[80:81]
	v_mov_b64_e32 v[130:131], v[120:121]
	v_mov_b64_e32 v[128:129], v[122:123]
	v_mov_b64_e32 v[126:127], v[106:107]
	v_mov_b64_e32 v[118:119], v[102:103]
	v_mov_b64_e32 v[124:125], v[108:109]
	v_mov_b64_e32 v[114:115], v[104:105]
	v_mov_b64_e32 v[116:117], v[110:111]
	v_mov_b64_e32 v[112:113], v[100:101]
	s_cbranch_scc1 .LBB0_768
	v_add_co_u32_e32 v114, vcc, 0xd061000, v134
	s_nop 1
	v_addc_co_u32_e32 v115, vcc, 0, v135, vcc
	v_add_co_u32_e32 v116, vcc, 0xd062000, v134
	s_nop 1
	v_addc_co_u32_e32 v117, vcc, 0, v135, vcc
	v_add_co_u32_e32 v124, vcc, 0xd05e000, v134
	s_nop 1
	v_addc_co_u32_e32 v125, vcc, 0, v135, vcc
	v_add_co_u32_e32 v126, vcc, 0xd05f000, v134
	global_load_dwordx2 v[112:113], v[114:115], off offset:1056
	s_nop 0
	global_load_dwordx2 v[114:115], v[114:115], off offset:3104
	s_nop 0
	global_load_dwordx2 v[118:119], v[116:117], off offset:1056
	s_nop 0
	global_load_dwordx2 v[116:117], v[124:125], off offset:1056
	v_addc_co_u32_e32 v127, vcc, 0, v135, vcc
	v_add_co_u32_e32 v128, vcc, 0x19010000, v132
	s_nop 1
	v_addc_co_u32_e32 v129, vcc, 0, v133, vcc
	v_add_co_u32_e32 v130, vcc, 0x1b010000, v132
	s_nop 1
	v_addc_co_u32_e32 v131, vcc, 0, v133, vcc
	global_load_dwordx2 v[124:125], v[124:125], off offset:3104
	s_nop 0
	global_load_dwordx2 v[126:127], v[126:127], off offset:1056
	s_nop 0
	global_load_dwordx2 v[128:129], v[128:129], off
	s_nop 0
	global_load_dwordx2 v[130:131], v[130:131], off
	v_add_co_u32_e32 v188, vcc, 0xd091000, v134
	s_nop 1
	v_addc_co_u32_e32 v189, vcc, 0, v135, vcc
	v_add_co_u32_e32 v190, vcc, 0xd092000, v134
	s_nop 1
	v_addc_co_u32_e32 v191, vcc, 0, v135, vcc
	v_add_co_u32_e32 v194, vcc, 0xd08e000, v134
	s_nop 1
	v_addc_co_u32_e32 v195, vcc, 0, v135, vcc
	v_add_co_u32_e32 v196, vcc, 0xd08f000, v134
	global_load_dwordx2 v[186:187], v[188:189], off offset:1056
	s_nop 0
	global_load_dwordx2 v[188:189], v[188:189], off offset:3104
	s_nop 0
	global_load_dwordx2 v[192:193], v[190:191], off offset:1056
	s_nop 0
	global_load_dwordx2 v[190:191], v[194:195], off offset:1056
	v_addc_co_u32_e32 v197, vcc, 0, v135, vcc
	v_add_co_u32_e32 v198, vcc, 0x19018000, v132
	s_nop 1
	v_addc_co_u32_e32 v199, vcc, 0, v133, vcc
	v_add_co_u32_e32 v200, vcc, 0x1b018000, v132
	s_nop 1
	v_addc_co_u32_e32 v201, vcc, 0, v133, vcc
	global_load_dwordx2 v[194:195], v[194:195], off offset:3104
	s_nop 0
	global_load_dwordx2 v[196:197], v[196:197], off offset:1056
	s_nop 0
	global_load_dwordx2 v[198:199], v[198:199], off
	s_nop 0
	global_load_dwordx2 v[200:201], v[200:201], off
	v_add_co_u32_e32 v204, vcc, 0xd0c1000, v134
	s_nop 1
	v_addc_co_u32_e32 v205, vcc, 0, v135, vcc
	v_add_co_u32_e32 v206, vcc, 0xd0c2000, v134
	s_nop 1
	v_addc_co_u32_e32 v207, vcc, 0, v135, vcc
	v_add_co_u32_e32 v210, vcc, 0xd0be000, v134
	s_nop 1
	v_addc_co_u32_e32 v211, vcc, 0, v135, vcc
	v_add_co_u32_e32 v212, vcc, 0xd0bf000, v134
	global_load_dwordx2 v[202:203], v[204:205], off offset:1056
	s_nop 0
	global_load_dwordx2 v[204:205], v[204:205], off offset:3104
	s_nop 0
	global_load_dwordx2 v[208:209], v[206:207], off offset:1056
	s_nop 0
	global_load_dwordx2 v[206:207], v[210:211], off offset:1056
	v_addc_co_u32_e32 v213, vcc, 0, v135, vcc
	v_add_co_u32_e32 v214, vcc, 0x19020000, v132
	s_nop 1
	v_addc_co_u32_e32 v215, vcc, 0, v133, vcc
	v_add_co_u32_e32 v216, vcc, 0x1b020000, v132
	s_nop 1
	v_addc_co_u32_e32 v217, vcc, 0, v133, vcc
	global_load_dwordx2 v[210:211], v[210:211], off offset:3104
	s_nop 0
	global_load_dwordx2 v[212:213], v[212:213], off offset:1056
	s_nop 0
	global_load_dwordx2 v[214:215], v[214:215], off
	s_nop 0
	global_load_dwordx2 v[216:217], v[216:217], off
	v_add_co_u32_e32 v220, vcc, 0xd0f1000, v134
	s_nop 1
	v_addc_co_u32_e32 v221, vcc, 0, v135, vcc
	v_add_co_u32_e32 v222, vcc, 0xd0f2000, v134
	s_nop 1
	v_addc_co_u32_e32 v223, vcc, 0, v135, vcc
	v_add_co_u32_e32 v226, vcc, 0xd0ee000, v134
	s_nop 1
	v_addc_co_u32_e32 v227, vcc, 0, v135, vcc
	v_add_co_u32_e32 v228, vcc, 0xd0ef000, v134
	global_load_dwordx2 v[218:219], v[220:221], off offset:1056
	s_nop 0
	global_load_dwordx2 v[220:221], v[220:221], off offset:3104
	s_nop 0
	global_load_dwordx2 v[224:225], v[222:223], off offset:1056
	s_nop 0
	global_load_dwordx2 v[222:223], v[226:227], off offset:1056
	v_addc_co_u32_e32 v229, vcc, 0, v135, vcc
	v_add_co_u32_e32 v230, vcc, 0x19028000, v132
	s_nop 1
	v_addc_co_u32_e32 v231, vcc, 0, v133, vcc
	v_add_co_u32_e32 v232, vcc, 0x1b028000, v132
	s_nop 1
	v_addc_co_u32_e32 v233, vcc, 0, v133, vcc
	global_load_dwordx2 v[226:227], v[226:227], off offset:3104
	s_nop 0
	global_load_dwordx2 v[228:229], v[228:229], off offset:1056
	s_nop 0
	global_load_dwordx2 v[230:231], v[230:231], off
	s_nop 0
	global_load_dwordx2 v[232:233], v[232:233], off

.LBB0_778:
	s_cmp_lg_u64 s[44:45], 0
	s_cbranch_scc0 .Lprod_late_w0
	s_waitcnt vmcnt(32)
	s_branch .Lprod_late_go

.LBB0_783:
	s_mov_b64 s[0:1], 0x800
	v_lshl_add_u64 v[78:79], v[78:79], 0, s[0:1]
	s_mov_b64 s[0:1], 0x10000
	s_add_i32 s63, s63, 1
	s_addk_i32 s62, 0x200
	s_add_i32 s16, s16, 32
	v_lshl_add_u64 v[80:81], v[80:81], 0, s[0:1]
	s_mov_b64 s[0:1], 0x60000
	s_cmp_eq_u32 s62, 0x10200
	v_lshl_add_u64 v[82:83], v[82:83], 0, s[0:1]
	s_waitcnt lgkmcnt(0)
	s_barrier
	s_cbranch_scc1 .LBB0_785
	s_waitcnt vmcnt(16)
	v_mov_b64_e32 v[84:85], v[200:201]
	v_mov_b64_e32 v[90:91], v[198:199]
	v_mov_b64_e32 v[92:93], v[196:197]
	v_mov_b64_e32 v[88:89], v[192:193]
	v_mov_b64_e32 v[94:95], v[194:195]
	v_mov_b64_e32 v[96:97], v[188:189]
	v_mov_b64_e32 v[98:99], v[190:191]
	v_mov_b64_e32 v[86:87], v[186:187]
	v_mov_b64_e32 v[120:121], v[130:131]
	v_mov_b64_e32 v[122:123], v[128:129]
	v_mov_b64_e32 v[106:107], v[126:127]
	v_mov_b64_e32 v[102:103], v[118:119]
	v_mov_b64_e32 v[108:109], v[124:125]
	v_mov_b64_e32 v[104:105], v[114:115]
	v_mov_b64_e32 v[110:111], v[116:117]
	v_mov_b64_e32 v[100:101], v[112:113]
	s_branch .LBB0_731
